# removed initial cg grid sync; P0 GEMV loads fully pipelined; P0 column blocks assigned XCD-contiguously
# speedup vs baseline: 1.0205x; 1.0205x over previous
.LBB0_17:
	s_load_dwordx16 s[36:51], s[0:1], 0x0
	s_cmp_lt_i32 s56, 1
	s_cselect_b64 s[0:1], -1, 0
	s_cmp_gt_i32 s57, 0
	s_cselect_b64 s[4:5], -1, 0
	s_and_b64 s[0:1], s[0:1], s[4:5]
	s_andn2_b64 vcc, exec, s[0:1]
	s_cbranch_vccnz .LBB0_81
	s_cmpk_gt_i32 s2, 0xff
	s_cbranch_scc1 .LBB0_27
	s_and_b32 s19, s2, 7
	s_lshl_b32 s19, s19, 5
	s_lshr_b32 s22, s2, 3
	s_or_b32 s19, s19, s22
	s_cmpk_eq_i32 s34, 0x100
	s_cselect_b32 s19, s19, s2
	v_mul_u32_u24_e32 v0, 0x2aab, v168
	v_lshrrev_b32_e32 v1, 16, v0
	v_mul_lo_u16_e32 v0, 6, v1
	s_movk_i32 s0, 0x1fe
	s_mov_b32 s4, 0x2aaaaaab
	v_sub_u16_e32 v0, v168, v0
	v_cmp_gt_u32_e32 vcc, s0, v168
	s_movk_i32 s0, 0x60
	v_mul_hi_u32 v6, v168, s4
	v_mov_b32_e32 v3, 0
	v_mad_u32_u24 v8, v1, s0, 0
	v_lshlrev_b32_e32 v0, 4, v0
	v_add_u32_e32 v13, 0xffffffab, v1
	v_lshlrev_b32_e32 v2, 2, v6
	v_mov_b32_e32 v1, v3
	s_movk_i32 s4, 0x6000
	v_lshl_add_u32 v12, v168, 2, 0
	s_waitcnt lgkmcnt(0)
	v_lshl_add_u64 v[4:5], s[38:39], 0, v[2:3]
	v_mad_u64_u32 v[2:3], s[4:5], v6, s4, v[0:1]
	v_cmp_gt_u32_e64 s[0:1], 24, v168
	v_lshl_add_u64 v[6:7], s[40:41], 0, v[2:3]
	s_mul_i32 s6, s19, 24
	s_mul_i32 s16, s34, 24
	s_mov_b64 s[8:9], 0x154
	s_mov_b64 s[10:11], 0x1fe000
	s_movk_i32 s17, 0x7aa
	v_add_u32_e32 v14, v8, v0
	v_add_u32_e32 v15, 0x200, v12
	v_add_u32_e32 v16, 0x400, v12
	v_add_u32_e32 v17, 0x800, v12
	v_add_u32_e32 v18, 0xc00, v12
	v_add_u32_e32 v19, 0xe00, v12
	v_add_u32_e32 v20, 0x1000, v12
	v_add_u32_e32 v21, 0x1400, v12
	v_add_u32_e32 v22, 0x1800, v12
	v_add_u32_e32 v23, 0x1a00, v12
	v_add_u32_e32 v24, 0x1c00, v12
	s_mov_b32 s18, s19
	s_branch .LBB0_21

.LBB0_21:
	s_and_saveexec_b64 s[12:13], vcc
	s_cbranch_execz .LBB0_25
	s_ashr_i32 s7, s6, 31
	v_mov_b32_e32 v0, 0
	v_lshl_add_u64 v[8:9], s[6:7], 2, v[6:7]
	v_mov_b64_e32 v[10:11], v[4:5]
	v_mov_b32_e32 v1, v0
	v_mov_b32_e32 v2, v0
	v_mov_b32_e32 v3, v0
	v_add_u32_e32 v25, 0x55, v13
	v_cmp_gt_u32_e64 s[4:5], 8, v25
	s_mov_b64 s[14:15], 0x2fd0000
	s_nop 1
	s_and_saveexec_b64 s[28:29], s[4:5]
	s_cbranch_execz .Lp0_no24a
	v_lshl_add_u64 v[26:27], v[8:9], 0, s[14:15]
	s_mov_b64 s[14:15], 0x1fe0
	global_load_dwordx4 v[128:131], v[26:27], off nt
	v_lshl_add_u64 v[26:27], v[10:11], 0, s[14:15]
	global_load_dword v218, v[26:27], off
.Lp0_no24a:
	s_or_b64 exec, exec, s[28:29]
	global_load_dwordx4 v[32:35], v[8:9], off nt
	global_load_dword v170, v[10:11], off
	v_lshl_add_u64 v[10:11], v[10:11], 0, s[8:9]
	v_lshl_add_u64 v[8:9], v[8:9], 0, s[10:11]
	global_load_dwordx4 v[36:39], v[8:9], off nt
	global_load_dword v172, v[10:11], off
	v_lshl_add_u64 v[10:11], v[10:11], 0, s[8:9]
	v_lshl_add_u64 v[8:9], v[8:9], 0, s[10:11]
	global_load_dwordx4 v[40:43], v[8:9], off nt
	global_load_dword v174, v[10:11], off
	v_lshl_add_u64 v[10:11], v[10:11], 0, s[8:9]
	v_lshl_add_u64 v[8:9], v[8:9], 0, s[10:11]
	global_load_dwordx4 v[44:47], v[8:9], off nt
	global_load_dword v176, v[10:11], off
	v_lshl_add_u64 v[10:11], v[10:11], 0, s[8:9]
	v_lshl_add_u64 v[8:9], v[8:9], 0, s[10:11]
	global_load_dwordx4 v[48:51], v[8:9], off nt
	global_load_dword v178, v[10:11], off
	v_lshl_add_u64 v[10:11], v[10:11], 0, s[8:9]
	v_lshl_add_u64 v[8:9], v[8:9], 0, s[10:11]
	global_load_dwordx4 v[52:55], v[8:9], off nt
	global_load_dword v180, v[10:11], off
	v_lshl_add_u64 v[10:11], v[10:11], 0, s[8:9]
	v_lshl_add_u64 v[8:9], v[8:9], 0, s[10:11]
	global_load_dwordx4 v[56:59], v[8:9], off nt
	global_load_dword v182, v[10:11], off
	v_lshl_add_u64 v[10:11], v[10:11], 0, s[8:9]
	v_lshl_add_u64 v[8:9], v[8:9], 0, s[10:11]
	global_load_dwordx4 v[60:63], v[8:9], off nt
	global_load_dword v184, v[10:11], off
	v_lshl_add_u64 v[10:11], v[10:11], 0, s[8:9]
	v_lshl_add_u64 v[8:9], v[8:9], 0, s[10:11]
	global_load_dwordx4 v[64:67], v[8:9], off nt
	global_load_dword v186, v[10:11], off
	v_lshl_add_u64 v[10:11], v[10:11], 0, s[8:9]
	v_lshl_add_u64 v[8:9], v[8:9], 0, s[10:11]
	global_load_dwordx4 v[68:71], v[8:9], off nt
	global_load_dword v188, v[10:11], off
	v_lshl_add_u64 v[10:11], v[10:11], 0, s[8:9]
	v_lshl_add_u64 v[8:9], v[8:9], 0, s[10:11]
	global_load_dwordx4 v[72:75], v[8:9], off nt
	global_load_dword v190, v[10:11], off
	v_lshl_add_u64 v[10:11], v[10:11], 0, s[8:9]
	v_lshl_add_u64 v[8:9], v[8:9], 0, s[10:11]
	global_load_dwordx4 v[76:79], v[8:9], off nt
	global_load_dword v192, v[10:11], off
	v_lshl_add_u64 v[10:11], v[10:11], 0, s[8:9]
	v_lshl_add_u64 v[8:9], v[8:9], 0, s[10:11]
	global_load_dwordx4 v[80:83], v[8:9], off nt
	global_load_dword v194, v[10:11], off
	v_lshl_add_u64 v[10:11], v[10:11], 0, s[8:9]
	v_lshl_add_u64 v[8:9], v[8:9], 0, s[10:11]
	global_load_dwordx4 v[84:87], v[8:9], off nt
	global_load_dword v196, v[10:11], off
	v_lshl_add_u64 v[10:11], v[10:11], 0, s[8:9]
	v_lshl_add_u64 v[8:9], v[8:9], 0, s[10:11]
	global_load_dwordx4 v[88:91], v[8:9], off nt
	global_load_dword v198, v[10:11], off
	v_lshl_add_u64 v[10:11], v[10:11], 0, s[8:9]
	v_lshl_add_u64 v[8:9], v[8:9], 0, s[10:11]
	global_load_dwordx4 v[92:95], v[8:9], off nt
	global_load_dword v200, v[10:11], off
	v_lshl_add_u64 v[10:11], v[10:11], 0, s[8:9]
	v_lshl_add_u64 v[8:9], v[8:9], 0, s[10:11]
	global_load_dwordx4 v[96:99], v[8:9], off nt
	global_load_dword v202, v[10:11], off
	v_lshl_add_u64 v[10:11], v[10:11], 0, s[8:9]
	v_lshl_add_u64 v[8:9], v[8:9], 0, s[10:11]
	global_load_dwordx4 v[100:103], v[8:9], off nt
	global_load_dword v204, v[10:11], off
	v_lshl_add_u64 v[10:11], v[10:11], 0, s[8:9]
	v_lshl_add_u64 v[8:9], v[8:9], 0, s[10:11]
	global_load_dwordx4 v[104:107], v[8:9], off nt
	global_load_dword v206, v[10:11], off
	v_lshl_add_u64 v[10:11], v[10:11], 0, s[8:9]
	v_lshl_add_u64 v[8:9], v[8:9], 0, s[10:11]
	global_load_dwordx4 v[108:111], v[8:9], off nt
	global_load_dword v208, v[10:11], off
	v_lshl_add_u64 v[10:11], v[10:11], 0, s[8:9]
	v_lshl_add_u64 v[8:9], v[8:9], 0, s[10:11]
	global_load_dwordx4 v[112:115], v[8:9], off nt
	global_load_dword v210, v[10:11], off
	v_lshl_add_u64 v[10:11], v[10:11], 0, s[8:9]
	v_lshl_add_u64 v[8:9], v[8:9], 0, s[10:11]
	global_load_dwordx4 v[116:119], v[8:9], off nt
	global_load_dword v212, v[10:11], off
	v_lshl_add_u64 v[10:11], v[10:11], 0, s[8:9]
	v_lshl_add_u64 v[8:9], v[8:9], 0, s[10:11]
	global_load_dwordx4 v[120:123], v[8:9], off nt
	global_load_dword v214, v[10:11], off
	v_lshl_add_u64 v[10:11], v[10:11], 0, s[8:9]
	v_lshl_add_u64 v[8:9], v[8:9], 0, s[10:11]
	global_load_dwordx4 v[124:127], v[8:9], off nt
	global_load_dword v216, v[10:11], off
	s_waitcnt vmcnt(46)
	v_pk_fma_f32 v[2:3], v[34:35], v[170:171], v[2:3] op_sel_hi:[1,0,1]
	v_pk_fma_f32 v[0:1], v[32:33], v[170:171], v[0:1] op_sel_hi:[1,0,1]
	s_waitcnt vmcnt(44)
	v_pk_fma_f32 v[2:3], v[38:39], v[172:173], v[2:3] op_sel_hi:[1,0,1]
	v_pk_fma_f32 v[0:1], v[36:37], v[172:173], v[0:1] op_sel_hi:[1,0,1]
	s_waitcnt vmcnt(42)
	v_pk_fma_f32 v[2:3], v[42:43], v[174:175], v[2:3] op_sel_hi:[1,0,1]
	v_pk_fma_f32 v[0:1], v[40:41], v[174:175], v[0:1] op_sel_hi:[1,0,1]
	s_waitcnt vmcnt(40)
	v_pk_fma_f32 v[2:3], v[46:47], v[176:177], v[2:3] op_sel_hi:[1,0,1]
	v_pk_fma_f32 v[0:1], v[44:45], v[176:177], v[0:1] op_sel_hi:[1,0,1]
	s_waitcnt vmcnt(38)
	v_pk_fma_f32 v[2:3], v[50:51], v[178:179], v[2:3] op_sel_hi:[1,0,1]
	v_pk_fma_f32 v[0:1], v[48:49], v[178:179], v[0:1] op_sel_hi:[1,0,1]
	s_waitcnt vmcnt(36)
	v_pk_fma_f32 v[2:3], v[54:55], v[180:181], v[2:3] op_sel_hi:[1,0,1]
	v_pk_fma_f32 v[0:1], v[52:53], v[180:181], v[0:1] op_sel_hi:[1,0,1]
	s_waitcnt vmcnt(34)
	v_pk_fma_f32 v[2:3], v[58:59], v[182:183], v[2:3] op_sel_hi:[1,0,1]
	v_pk_fma_f32 v[0:1], v[56:57], v[182:183], v[0:1] op_sel_hi:[1,0,1]
	s_waitcnt vmcnt(32)
	v_pk_fma_f32 v[2:3], v[62:63], v[184:185], v[2:3] op_sel_hi:[1,0,1]
	v_pk_fma_f32 v[0:1], v[60:61], v[184:185], v[0:1] op_sel_hi:[1,0,1]
	s_waitcnt vmcnt(30)
	v_pk_fma_f32 v[2:3], v[66:67], v[186:187], v[2:3] op_sel_hi:[1,0,1]
	v_pk_fma_f32 v[0:1], v[64:65], v[186:187], v[0:1] op_sel_hi:[1,0,1]
	s_waitcnt vmcnt(28)
	v_pk_fma_f32 v[2:3], v[70:71], v[188:189], v[2:3] op_sel_hi:[1,0,1]
	v_pk_fma_f32 v[0:1], v[68:69], v[188:189], v[0:1] op_sel_hi:[1,0,1]
	s_waitcnt vmcnt(26)
	v_pk_fma_f32 v[2:3], v[74:75], v[190:191], v[2:3] op_sel_hi:[1,0,1]
	v_pk_fma_f32 v[0:1], v[72:73], v[190:191], v[0:1] op_sel_hi:[1,0,1]
	s_waitcnt vmcnt(24)
	v_pk_fma_f32 v[2:3], v[78:79], v[192:193], v[2:3] op_sel_hi:[1,0,1]
	v_pk_fma_f32 v[0:1], v[76:77], v[192:193], v[0:1] op_sel_hi:[1,0,1]
	s_waitcnt vmcnt(22)
	v_pk_fma_f32 v[2:3], v[82:83], v[194:195], v[2:3] op_sel_hi:[1,0,1]
	v_pk_fma_f32 v[0:1], v[80:81], v[194:195], v[0:1] op_sel_hi:[1,0,1]
	s_waitcnt vmcnt(20)
	v_pk_fma_f32 v[2:3], v[86:87], v[196:197], v[2:3] op_sel_hi:[1,0,1]
	v_pk_fma_f32 v[0:1], v[84:85], v[196:197], v[0:1] op_sel_hi:[1,0,1]
	s_waitcnt vmcnt(18)
	v_pk_fma_f32 v[2:3], v[90:91], v[198:199], v[2:3] op_sel_hi:[1,0,1]
	v_pk_fma_f32 v[0:1], v[88:89], v[198:199], v[0:1] op_sel_hi:[1,0,1]
	s_waitcnt vmcnt(16)
	v_pk_fma_f32 v[2:3], v[94:95], v[200:201], v[2:3] op_sel_hi:[1,0,1]
	v_pk_fma_f32 v[0:1], v[92:93], v[200:201], v[0:1] op_sel_hi:[1,0,1]
	s_waitcnt vmcnt(14)
	v_pk_fma_f32 v[2:3], v[98:99], v[202:203], v[2:3] op_sel_hi:[1,0,1]
	v_pk_fma_f32 v[0:1], v[96:97], v[202:203], v[0:1] op_sel_hi:[1,0,1]
	s_waitcnt vmcnt(12)
	v_pk_fma_f32 v[2:3], v[102:103], v[204:205], v[2:3] op_sel_hi:[1,0,1]
	v_pk_fma_f32 v[0:1], v[100:101], v[204:205], v[0:1] op_sel_hi:[1,0,1]
	s_waitcnt vmcnt(10)
	v_pk_fma_f32 v[2:3], v[106:107], v[206:207], v[2:3] op_sel_hi:[1,0,1]
	v_pk_fma_f32 v[0:1], v[104:105], v[206:207], v[0:1] op_sel_hi:[1,0,1]
	s_waitcnt vmcnt(8)
	v_pk_fma_f32 v[2:3], v[110:111], v[208:209], v[2:3] op_sel_hi:[1,0,1]
	v_pk_fma_f32 v[0:1], v[108:109], v[208:209], v[0:1] op_sel_hi:[1,0,1]
	s_waitcnt vmcnt(6)
	v_pk_fma_f32 v[2:3], v[114:115], v[210:211], v[2:3] op_sel_hi:[1,0,1]
	v_pk_fma_f32 v[0:1], v[112:113], v[210:211], v[0:1] op_sel_hi:[1,0,1]
	s_waitcnt vmcnt(4)
	v_pk_fma_f32 v[2:3], v[118:119], v[212:213], v[2:3] op_sel_hi:[1,0,1]
	v_pk_fma_f32 v[0:1], v[116:117], v[212:213], v[0:1] op_sel_hi:[1,0,1]
	s_waitcnt vmcnt(2)
	v_pk_fma_f32 v[2:3], v[122:123], v[214:215], v[2:3] op_sel_hi:[1,0,1]
	v_pk_fma_f32 v[0:1], v[120:121], v[214:215], v[0:1] op_sel_hi:[1,0,1]
	s_waitcnt vmcnt(0)
	v_pk_fma_f32 v[2:3], v[126:127], v[216:217], v[2:3] op_sel_hi:[1,0,1]
	v_pk_fma_f32 v[0:1], v[124:125], v[216:217], v[0:1] op_sel_hi:[1,0,1]
	s_and_saveexec_b64 s[28:29], s[4:5]
	s_cbranch_execz .Lp0_no24b
	v_pk_fma_f32 v[2:3], v[130:131], v[218:219], v[2:3] op_sel_hi:[1,0,1]
	v_pk_fma_f32 v[0:1], v[128:129], v[218:219], v[0:1] op_sel_hi:[1,0,1]
.Lp0_no24b:
	s_or_b64 exec, exec, s[28:29]
	ds_write_b128 v14, v[0:3]
